# 6 of 16 plain-epilogue H stores deferred into the next unit's first 3 K-loop iterations (data parked in VGPRs P1 does not use), on top of saddr K-loop/epilogue
# speedup vs baseline: 1.0058x; 1.0058x over previous
.LBB0_95:
	s_mov_b32 s2, s0
	v_writelane_b32 v254, s2, 36
	s_lshl_b32 s0, s0, 3
	v_readlane_b32 s4, v252, 6
	v_writelane_b32 v254, s3, 37
	s_or_b32 s2, s0, 1
	v_readlane_b32 s5, v252, 7
	s_cmp_le_i32 s4, s2
	v_writelane_b32 v254, s0, 38
	s_cselect_b64 s[0:1], -1, 0
	s_cmp_lt_i32 s2, s5
	s_cselect_b64 s[4:5], -1, 0
	s_and_b64 s[10:11], s[0:1], s[4:5]
	s_andn2_b64 vcc, exec, s[10:11]
	s_cbranch_vccnz .LBB0_184
	s_mov_b32 s98, 0
	s_mov_b64 s[86:87], 0
	v_readlane_b32 s0, v254, 20
	v_readlane_b32 s2, v252, 2
	v_readlane_b32 s16, v252, 15
	v_mov_b32_e32 v0, s0
	s_waitcnt vmcnt(19)
	ds_read_b64 v[2:3], v0
	v_mov_b32_e32 v0, v1
	v_readlane_b32 s0, v252, 16
	v_mbcnt_lo_u32_b32 v0, -1, v0
	v_readlane_b32 s1, v252, 17
	s_waitcnt lgkmcnt(0)
	v_readfirstlane_b32 s37, v3
	v_readfirstlane_b32 s36, v2
	v_mbcnt_hi_u32_b32 v2, -1, v0
	s_andn2_b64 vcc, exec, s[0:1]
	s_cbranch_vccnz .LBB0_122
	v_readlane_b32 s0, v254, 36
	v_readlane_b32 s1, v254, 37
	s_mul_i32 s18, s0, 0x2680000
	s_add_u32 s4, s36, 0x28d00000
	s_addc_u32 s5, s37, 0
	s_lshl_b64 s[0:1], s[18:19], 1
	s_add_u32 s0, s36, s0
	s_addc_u32 s1, s37, s1
	s_add_u32 s6, s0, 0x100000
	s_addc_u32 s7, s1, 0
	s_lshl_b32 s8, s16, 10
	v_lshlrev_b32_e32 v3, 4, v2
	s_waitcnt vmcnt(9)
	v_add_u32_e32 v4, s8, v3
	v_add_u32_e32 v5, 0x2000, v4
	v_ashrrev_i32_e32 v0, 31, v5
	v_lshrrev_b32_e32 v0, 22, v0
	v_add_u32_e32 v0, v5, v0
	v_ashrrev_i32_e32 v0, 10, v0
	v_mul_i32_i24_e32 v6, 0x400, v0
	v_sub_u32_e32 v5, v5, v6
	v_lshrrev_b32_e32 v6, 4, v5
	v_bitop3_b32 v5, v6, v5, 32 bitop3:0x6c
	v_ashrrev_i32_e32 v6, 31, v5
	v_lshrrev_b32_e32 v6, 26, v6
	v_add_u32_e32 v6, v5, v6
	v_lshlrev_b32_e32 v7, 3, v0
	v_ashrrev_i32_e32 v12, 6, v6
	v_and_b32_e32 v7, -16, v7
	v_and_b32_e32 v6, 0xffc0, v6
	v_add_u32_e32 v7, v12, v7
	v_sub_u32_e32 v5, v5, v6
	s_waitcnt vmcnt(8)
	v_and_b32_e32 v8, 3, v12
	s_mov_b32 s0, 0xfffe0
	v_lshrrev_b32_e32 v9, 2, v7
	v_lshlrev_b32_e32 v10, 1, v7
	v_lshrrev_b16_e32 v6, 7, v5
	v_and_or_b32 v8, v7, s0, v8
	v_and_b32_e32 v9, 4, v9
	v_and_b32_e32 v10, 24, v10
	v_and_b32_e32 v6, 1, v6
	v_or3_b32 v8, v8, v9, v10
	v_add_u16_e32 v5, v5, v6
	v_mov_b32_e32 v10, 1
	v_lshlrev_b32_e32 v9, 5, v0
	v_ashrrev_i16_sdwa v5, v10, sext(v5) dst_sel:DWORD dst_unused:UNUSED_PAD src0_sel:DWORD src1_sel:BYTE_0
	v_and_b32_e32 v9, 32, v9
	v_bfe_i32 v13, v5, 0, 16
	v_add_lshl_u32 v5, v9, v13, 1
	v_lshl_add_u32 v130, v8, 12, v5
	v_lshl_add_u32 v132, v7, 12, v5
	v_ashrrev_i32_e32 v5, 31, v4
	v_lshrrev_b32_e32 v5, 22, v5
	v_add_u32_e32 v5, v4, v5
	s_waitcnt vmcnt(0)
	v_ashrrev_i32_e32 v14, 10, v5
	v_mul_i32_i24_e32 v5, 0x400, v14
	v_sub_u32_e32 v4, v4, v5
	v_lshrrev_b32_e32 v5, 4, v4
	v_bitop3_b32 v4, v5, v4, 32 bitop3:0x6c
	v_ashrrev_i32_e32 v5, 31, v4
	v_lshrrev_b32_e32 v5, 26, v5
	v_add_u32_e32 v5, v4, v5
	v_lshlrev_b32_e32 v6, 3, v14
	v_ashrrev_i32_e32 v15, 6, v5
	v_and_b32_e32 v6, -16, v6
	v_add_u32_e32 v6, v15, v6
	v_and_b32_e32 v7, 3, v15
	v_lshrrev_b32_e32 v8, 2, v6
	v_lshlrev_b32_e32 v9, 1, v6
	v_and_b32_e32 v5, 0xc0, v5
	v_and_or_b32 v7, v6, s0, v7
	v_and_b32_e32 v8, 4, v8
	v_and_b32_e32 v9, 24, v9
	v_sub_u32_e32 v4, v4, v5
	s_ashr_i32 s18, s16, 2
	v_or3_b32 v7, v7, v8, v9
	v_lshlrev_b32_e32 v8, 5, v14
	v_ashrrev_i16_sdwa v4, v10, sext(v4) dst_sel:DWORD dst_unused:UNUSED_PAD src0_sel:DWORD src1_sel:BYTE_0
	v_readlane_b32 s0, v254, 6
	v_and_b32_e32 v8, 32, v8
	v_bfe_i32 v16, v4, 0, 16
	v_readlane_b32 s1, v254, 7
	s_add_u32 s0, s6, s0
	v_add_lshl_u32 v4, v8, v16, 1
	s_addc_u32 s1, s7, s1
	s_add_i32 s9, s8, 0
	v_lshl_add_u32 v134, v7, 12, v4
	s_add_i32 m0, s9, 0x10000
	v_lshl_add_u32 v136, v6, 12, v4
	global_load_lds_dwordx4 v134, s[0:1]
	s_add_i32 m0, s9, 0x12000
	s_add_u32 s12, s0, 0x80000
	global_load_lds_dwordx4 v130, s[0:1]
	s_addc_u32 s13, s1, 0
	s_add_i32 m0, s9, 0x14000
	v_mov_b32_e32 v135, v1
	global_load_lds_dwordx4 v134, s[12:13]
	s_add_i32 m0, s9, 0x16000
	v_mov_b32_e32 v131, v1
	global_load_lds_dwordx4 v130, s[12:13]
	v_readlane_b32 s12, v254, 2
	v_readlane_b32 s13, v254, 3
	s_add_u32 s48, s4, s12
	s_addc_u32 s49, s5, s13
	s_add_i32 s28, s9, 0x2000
	s_mov_b32 m0, s9
	s_add_u32 s12, s48, 0x80000
	global_load_lds_dwordx4 v136, s[48:49]
	s_mov_b32 m0, s28
	s_addc_u32 s13, s49, 0
	s_add_i32 s29, s9, 0x4000
	global_load_lds_dwordx4 v132, s[48:49]
	s_mov_b32 m0, s29
	s_add_i32 s35, s9, 0x6000
	global_load_lds_dwordx4 v136, s[12:13]
	s_mov_b32 m0, s35
	v_mov_b32_e32 v137, v1
	global_load_lds_dwordx4 v132, s[12:13]
	v_mov_b32_e32 v133, v1
	s_cmp_eq_u32 s18, 1
	v_lshl_add_u64 v[10:11], s[0:1], 0, v[134:135]
	v_lshl_add_u64 v[8:9], s[0:1], 0, v[130:131]
	v_lshl_add_u64 v[4:5], s[48:49], 0, v[136:137]
	s_cselect_b64 s[12:13], -1, 0
	s_cmp_lg_u32 s18, 1
	v_lshl_add_u64 v[6:7], s[48:49], 0, v[132:133]
	s_cbranch_scc1 .LBB0_99
	s_barrier

.LBB0_104:
	s_add_i32 s30, s38, 0x44
	s_add_i32 s31, s38, 0xffffffbc
	s_cmp_lt_u32 s31, 8
	s_cselect_b32 s31, s31, s38
	s_cmp_lt_i32 s38, 8
	s_cselect_b32 s38, s30, s31
	s_ashr_i32 s41, s40, 31
	s_lshl_b64 s[30:31], s[40:41], 20
	s_add_u32 s42, s4, s30
	s_addc_u32 s43, s5, s31
	s_and_b64 s[30:31], s[36:37], exec
	s_cselect_b32 s41, s43, s49
	s_cselect_b32 s47, s42, s48
	s_ashr_i32 s39, s38, 31
	s_lshl_b64 s[30:31], s[38:39], 20
	s_add_u32 s44, s6, s30
	s_addc_u32 s45, s7, s31
	s_and_b64 s[30:31], s[36:37], exec
	s_cselect_b32 s39, s45, s1
	s_cselect_b32 s55, s44, s0
	s_add_u32 s60, s0, 0x100
	s_addc_u32 s61, s1, 0
	s_add_u32 s0, s48, 0x80080
	s_addc_u32 s1, s49, 0
	s_mov_b32 s62, -2
	s_add_u32 s30, s0, 0xfff80080
	s_addc_u32 s31, s1, -1
	s_add_i32 s63, 0, 0x10000
	s_cmp_eq_u32 s62, 28
	s_cselect_b32 s51, s41, s31
	s_cselect_b32 s50, s47, s30
	v_add_u32_e32 v150, s63, v153
	s_cselect_b32 s49, s39, s61
	s_cselect_b32 s48, s55, s60
	s_add_i32 s64, 0, 0x14000
	ds_read_b128 v[146:149], v150
	ds_read_b128 v[156:159], v150 offset:1024
	ds_read_b128 v[160:163], v150 offset:2048
	ds_read_b128 v[174:177], v150 offset:3072
	v_add_u32_e32 v150, s64, v153
	ds_read_b128 v[178:181], v150
	ds_read_b128 v[182:185], v150 offset:1024
	ds_read_b128 v[186:189], v150 offset:2048
	ds_read_b128 v[190:193], v150 offset:3072
	s_add_i32 m0, s9, 0xc000
	ds_read_b128 v[194:197], v155
	ds_read_b128 v[198:201], v155 offset:1024
	ds_read_b128 v[202:205], v155 offset:2048
	ds_read_b128 v[206:209], v155 offset:3072
	ds_read_b128 v[218:221], v155 offset:4096
	ds_read_b128 v[222:225], v155 offset:5120
	ds_read_b128 v[226:229], v155 offset:6144
	ds_read_b128 v[230:233], v155 offset:7168
	global_load_lds_dwordx4 v144, s[0:1]
	s_add_i32 m0, s9, 0xe000
	s_nop 0
	global_load_lds_dwordx4 v142, s[0:1]
	s_cmp_eq_u32 s98, 8
	s_cbranch_scc1 .Lp1d3_w1_8
	s_cmp_eq_u32 s98, 10
	s_cbranch_scc1 .Lp1d3_w1_10
	s_cmp_eq_u32 s98, 16
	s_cbranch_scc1 .Lp1d3_w1_16
	s_waitcnt vmcnt(8)
	s_branch .Lp1d3_w1_done
.Lp1d3_w1_8:
	s_waitcnt vmcnt(16)
	s_branch .Lp1d3_w1_done
.Lp1d3_w1_10:
	s_waitcnt vmcnt(18)
	s_branch .Lp1d3_w1_done

.Lp1d3_w1_done:
	s_waitcnt lgkmcnt(0)
	s_barrier
	s_setprio 1
	s_waitcnt lgkmcnt(0)
	v_mfma_f32_16x16x32_bf16 v[70:73], v[146:149], v[194:197], 0
	v_mfma_f32_16x16x32_bf16 v[66:69], v[160:163], v[194:197], 0
	s_mov_b64 exec, s[86:87]
	global_store_dwordx4 v234, v[210:213], s[14:15]
	s_mov_b64 exec, -1
	v_mfma_f32_16x16x32_bf16 v[62:65], v[146:149], v[202:205], 0
	v_mfma_f32_16x16x32_bf16 v[58:61], v[160:163], v[202:205], 0
	v_mfma_f32_16x16x32_bf16 v[50:53], v[146:149], v[218:221], 0
	v_mfma_f32_16x16x32_bf16 v[46:49], v[160:163], v[218:221], 0
	v_mfma_f32_16x16x32_bf16 v[42:45], v[146:149], v[226:229], 0
	v_mfma_f32_16x16x32_bf16 v[38:41], v[160:163], v[226:229], 0
	v_mfma_f32_16x16x32_bf16 v[70:73], v[156:159], v[198:201], v[70:73]
	v_mfma_f32_16x16x32_bf16 v[66:69], v[174:177], v[198:201], v[66:69]
	v_mfma_f32_16x16x32_bf16 v[62:65], v[156:159], v[206:209], v[62:65]
	v_mfma_f32_16x16x32_bf16 v[58:61], v[174:177], v[206:209], v[58:61]
	v_mfma_f32_16x16x32_bf16 v[50:53], v[156:159], v[222:225], v[50:53]
	v_mfma_f32_16x16x32_bf16 v[46:49], v[174:177], v[222:225], v[46:49]
	v_mfma_f32_16x16x32_bf16 v[42:45], v[156:159], v[230:233], v[42:45]
	v_mfma_f32_16x16x32_bf16 v[38:41], v[174:177], v[230:233], v[38:41]
	s_setprio 0
	s_setprio 1
	v_mfma_f32_16x16x32_bf16 v[126:129], v[178:181], v[194:197], 0
	v_mfma_f32_16x16x32_bf16 v[122:125], v[186:189], v[194:197], 0
	v_mfma_f32_16x16x32_bf16 v[118:121], v[178:181], v[202:205], 0
	v_mfma_f32_16x16x32_bf16 v[114:117], v[186:189], v[202:205], 0
	v_mfma_f32_16x16x32_bf16 v[110:113], v[178:181], v[218:221], 0
	v_mfma_f32_16x16x32_bf16 v[106:109], v[186:189], v[218:221], 0
	v_mfma_f32_16x16x32_bf16 v[102:105], v[178:181], v[226:229], 0
	v_mfma_f32_16x16x32_bf16 v[98:101], v[186:189], v[226:229], 0
	v_mfma_f32_16x16x32_bf16 v[126:129], v[182:185], v[198:201], v[126:129]
	v_mfma_f32_16x16x32_bf16 v[122:125], v[190:193], v[198:201], v[122:125]
	v_mfma_f32_16x16x32_bf16 v[118:121], v[182:185], v[206:209], v[118:121]
	v_mfma_f32_16x16x32_bf16 v[114:117], v[190:193], v[206:209], v[114:117]
	v_mfma_f32_16x16x32_bf16 v[110:113], v[182:185], v[222:225], v[110:113]
	v_mfma_f32_16x16x32_bf16 v[106:109], v[190:193], v[222:225], v[106:109]
	v_mfma_f32_16x16x32_bf16 v[102:105], v[182:185], v[230:233], v[102:105]
	v_mfma_f32_16x16x32_bf16 v[98:101], v[190:193], v[230:233], v[98:101]
	s_setprio 0
	s_barrier
	s_add_i32 s30, s63, s8
	s_mov_b32 m0, s30
	ds_read_b128 v[194:197], v155 offset:16384
	ds_read_b128 v[198:201], v155 offset:17408
	ds_read_b128 v[202:205], v155 offset:18432
	ds_read_b128 v[206:209], v155 offset:19456
	ds_read_b128 v[218:221], v155 offset:20480
	ds_read_b128 v[222:225], v155 offset:21504
	ds_read_b128 v[226:229], v155 offset:22528
	ds_read_b128 v[230:233], v155 offset:23552
	global_load_lds_dwordx4 v134, s[48:49]
	s_add_i32 m0, s30, 0x2000
	s_add_u32 s30, s48, 0x80000
	s_mov_b64 s[82:83], s[48:49]
	s_addc_u32 s31, s49, 0
	s_add_i32 s63, s64, s8
	global_load_lds_dwordx4 v130, s[48:49]
	s_mov_b32 m0, s63
	s_nop 0
	global_load_lds_dwordx4 v134, s[30:31]
	s_add_i32 m0, s63, 0x2000
	s_nop 0
	global_load_lds_dwordx4 v130, s[30:31]
	s_mov_b32 m0, s9
	s_nop 0
	global_load_lds_dwordx4 v136, s[50:51]
	s_mov_b32 m0, s28
	s_nop 0
	global_load_lds_dwordx4 v132, s[50:51]
	s_cmp_eq_u32 s98, 8
	s_cbranch_scc1 .Lp1d3_w2_8
	s_cmp_eq_u32 s98, 10
	s_cbranch_scc1 .Lp1d3_w2_10
	s_cmp_eq_u32 s98, 16
	s_cbranch_scc1 .Lp1d3_w2_16
	s_waitcnt vmcnt(9)
	s_branch .Lp1d3_w2_done
.Lp1d3_w2_8:
	s_waitcnt vmcnt(17)
	s_branch .Lp1d3_w2_done
.Lp1d3_w2_10:
	s_waitcnt vmcnt(19)
	s_branch .Lp1d3_w2_done
.Lp1d3_w2_16:
	s_waitcnt vmcnt(25)
.Lp1d3_w2_done:
	s_waitcnt lgkmcnt(0)
	s_barrier
	s_setprio 1
	s_waitcnt lgkmcnt(0)
	v_mfma_f32_16x16x32_bf16 v[30:33], v[146:149], v[194:197], 0
	v_mfma_f32_16x16x32_bf16 v[26:29], v[160:163], v[194:197], 0
	v_mfma_f32_16x16x32_bf16 v[22:25], v[146:149], v[202:205], 0
	v_mfma_f32_16x16x32_bf16 v[18:21], v[160:163], v[202:205], 0
	v_mfma_f32_16x16x32_bf16 v[14:17], v[146:149], v[218:221], 0
	v_mfma_f32_16x16x32_bf16 v[10:13], v[160:163], v[218:221], 0
	v_mfma_f32_16x16x32_bf16 v[6:9], v[146:149], v[226:229], 0
	v_mfma_f32_16x16x32_bf16 v[2:5], v[160:163], v[226:229], 0
	v_mfma_f32_16x16x32_bf16 v[30:33], v[156:159], v[198:201], v[30:33]
	v_mfma_f32_16x16x32_bf16 v[26:29], v[174:177], v[198:201], v[26:29]
	v_mfma_f32_16x16x32_bf16 v[22:25], v[156:159], v[206:209], v[22:25]
	v_mfma_f32_16x16x32_bf16 v[18:21], v[174:177], v[206:209], v[18:21]
	v_mfma_f32_16x16x32_bf16 v[14:17], v[156:159], v[222:225], v[14:17]
	v_mfma_f32_16x16x32_bf16 v[10:13], v[174:177], v[222:225], v[10:13]
	v_mfma_f32_16x16x32_bf16 v[6:9], v[156:159], v[230:233], v[6:9]
	v_mfma_f32_16x16x32_bf16 v[2:5], v[174:177], v[230:233], v[2:5]
	s_setprio 0
	s_setprio 1
	v_mfma_f32_16x16x32_bf16 v[94:97], v[178:181], v[194:197], 0
	v_mfma_f32_16x16x32_bf16 v[90:93], v[186:189], v[194:197], 0
	v_mfma_f32_16x16x32_bf16 v[86:89], v[178:181], v[202:205], 0
	v_mfma_f32_16x16x32_bf16 v[82:85], v[186:189], v[202:205], 0
	v_mfma_f32_16x16x32_bf16 v[78:81], v[178:181], v[218:221], 0
	v_mfma_f32_16x16x32_bf16 v[74:77], v[186:189], v[218:221], 0
	v_mfma_f32_16x16x32_bf16 v[54:57], v[178:181], v[226:229], 0
	v_mfma_f32_16x16x32_bf16 v[34:37], v[186:189], v[226:229], 0
	v_mfma_f32_16x16x32_bf16 v[94:97], v[182:185], v[198:201], v[94:97]
	v_mfma_f32_16x16x32_bf16 v[90:93], v[190:193], v[198:201], v[90:93]
	v_mfma_f32_16x16x32_bf16 v[86:89], v[182:185], v[206:209], v[86:89]
	v_mfma_f32_16x16x32_bf16 v[82:85], v[190:193], v[206:209], v[82:85]
	v_mfma_f32_16x16x32_bf16 v[78:81], v[182:185], v[222:225], v[78:81]
	v_mfma_f32_16x16x32_bf16 v[74:77], v[190:193], v[222:225], v[74:77]
	v_mfma_f32_16x16x32_bf16 v[54:57], v[182:185], v[230:233], v[54:57]
	v_mfma_f32_16x16x32_bf16 v[34:37], v[190:193], v[230:233], v[34:37]
	s_setprio 0
	s_barrier
	s_add_i32 s63, 0, 0x18000
	v_add_u32_e32 v172, s63, v153
	s_add_i32 s64, 0, 0x1c000
	ds_read_b128 v[146:149], v172
	ds_read_b128 v[156:159], v172 offset:1024
	ds_read_b128 v[160:163], v172 offset:2048
	ds_read_b128 v[174:177], v172 offset:3072
	v_add_u32_e32 v172, s64, v153
	ds_read_b128 v[178:181], v172
	ds_read_b128 v[182:185], v172 offset:1024
	ds_read_b128 v[186:189], v172 offset:2048
	ds_read_b128 v[190:193], v172 offset:3072
	s_add_u32 s30, s50, 0x80000
	s_addc_u32 s31, s51, 0
	s_mov_b32 m0, s29
	ds_read_b128 v[194:197], v155 offset:32768
	ds_read_b128 v[198:201], v155 offset:33792
	ds_read_b128 v[202:205], v155 offset:34816
	ds_read_b128 v[206:209], v155 offset:35840
	ds_read_b128 v[218:221], v155 offset:36864
	ds_read_b128 v[222:225], v155 offset:37888
	ds_read_b128 v[226:229], v155 offset:38912
	ds_read_b128 v[230:233], v155 offset:39936
	global_load_lds_dwordx4 v136, s[30:31]
	s_mov_b32 m0, s35
	s_nop 0
	global_load_lds_dwordx4 v132, s[30:31]
	s_waitcnt vmcnt(9)
	s_waitcnt lgkmcnt(0)
	s_barrier
	s_setprio 1
	s_waitcnt lgkmcnt(0)
	v_mfma_f32_16x16x32_bf16 v[70:73], v[146:149], v[194:197], v[70:73]
	v_mfma_f32_16x16x32_bf16 v[66:69], v[160:163], v[194:197], v[66:69]
	s_mov_b64 exec, s[86:87]
	global_store_dwordx4 v234, v[214:217], s[14:15] offset:256
	s_mov_b64 exec, -1
	v_mfma_f32_16x16x32_bf16 v[62:65], v[146:149], v[202:205], v[62:65]
	v_mfma_f32_16x16x32_bf16 v[58:61], v[160:163], v[202:205], v[58:61]
	v_mfma_f32_16x16x32_bf16 v[50:53], v[146:149], v[218:221], v[50:53]
	v_mfma_f32_16x16x32_bf16 v[46:49], v[160:163], v[218:221], v[46:49]
	v_mfma_f32_16x16x32_bf16 v[42:45], v[146:149], v[226:229], v[42:45]
	v_mfma_f32_16x16x32_bf16 v[38:41], v[160:163], v[226:229], v[38:41]
	v_mfma_f32_16x16x32_bf16 v[70:73], v[156:159], v[198:201], v[70:73]
	v_mfma_f32_16x16x32_bf16 v[66:69], v[174:177], v[198:201], v[66:69]
	v_mfma_f32_16x16x32_bf16 v[62:65], v[156:159], v[206:209], v[62:65]
	v_mfma_f32_16x16x32_bf16 v[58:61], v[174:177], v[206:209], v[58:61]
	v_mfma_f32_16x16x32_bf16 v[50:53], v[156:159], v[222:225], v[50:53]
	v_mfma_f32_16x16x32_bf16 v[46:49], v[174:177], v[222:225], v[46:49]
	v_mfma_f32_16x16x32_bf16 v[42:45], v[156:159], v[230:233], v[42:45]
	v_mfma_f32_16x16x32_bf16 v[38:41], v[174:177], v[230:233], v[38:41]
	s_setprio 0
	s_setprio 1
	v_mfma_f32_16x16x32_bf16 v[126:129], v[178:181], v[194:197], v[126:129]
	v_mfma_f32_16x16x32_bf16 v[122:125], v[186:189], v[194:197], v[122:125]
	v_mfma_f32_16x16x32_bf16 v[118:121], v[178:181], v[202:205], v[118:121]
	v_mfma_f32_16x16x32_bf16 v[114:117], v[186:189], v[202:205], v[114:117]
	v_mfma_f32_16x16x32_bf16 v[110:113], v[178:181], v[218:221], v[110:113]
	v_mfma_f32_16x16x32_bf16 v[106:109], v[186:189], v[218:221], v[106:109]
	v_mfma_f32_16x16x32_bf16 v[102:105], v[178:181], v[226:229], v[102:105]
	v_mfma_f32_16x16x32_bf16 v[98:101], v[186:189], v[226:229], v[98:101]
	v_mfma_f32_16x16x32_bf16 v[126:129], v[182:185], v[198:201], v[126:129]
	v_mfma_f32_16x16x32_bf16 v[122:125], v[190:193], v[198:201], v[122:125]
	v_mfma_f32_16x16x32_bf16 v[118:121], v[182:185], v[206:209], v[118:121]
	v_mfma_f32_16x16x32_bf16 v[114:117], v[190:193], v[206:209], v[114:117]
	v_mfma_f32_16x16x32_bf16 v[110:113], v[182:185], v[222:225], v[110:113]
	v_mfma_f32_16x16x32_bf16 v[106:109], v[190:193], v[222:225], v[106:109]
	v_mfma_f32_16x16x32_bf16 v[102:105], v[182:185], v[230:233], v[102:105]
	v_mfma_f32_16x16x32_bf16 v[98:101], v[190:193], v[230:233], v[98:101]
	s_setprio 0
	s_barrier
	s_add_i32 s30, s63, s8
	s_add_i32 m0, s30, 0xffffff80
	ds_read_b128 v[194:197], v155 offset:49152
	ds_read_b128 v[198:201], v155 offset:50176
	ds_read_b128 v[202:205], v155 offset:51200
	ds_read_b128 v[206:209], v155 offset:52224
	ds_read_b128 v[218:221], v155 offset:53248
	ds_read_b128 v[222:225], v155 offset:54272
	ds_read_b128 v[226:229], v155 offset:55296
	ds_read_b128 v[230:233], v155 offset:56320
	global_load_lds_dwordx4 v134, s[48:49] offset:128
	s_add_i32 m0, s30, 0x1f80
	s_add_u32 s30, s48, 0x80080
	s_addc_u32 s31, s49, 0
	s_add_i32 s48, s64, s8
	global_load_lds_dwordx4 v130, s[82:83] offset:128
	s_mov_b32 m0, s48
	s_nop 0
	global_load_lds_dwordx4 v134, s[30:31]
	s_add_i32 m0, s48, 0x2000
	s_nop 0
	global_load_lds_dwordx4 v130, s[30:31]
	s_add_i32 m0, s52, 0xffffff80
	s_nop 0
	global_load_lds_dwordx4 v136, s[50:51] offset:128
	s_add_i32 m0, s53, 0xffffff80
	s_nop 0
	global_load_lds_dwordx4 v132, s[50:51] offset:128
	s_waitcnt vmcnt(9)
	s_waitcnt lgkmcnt(0)
	s_barrier
	s_setprio 1
	s_waitcnt lgkmcnt(0)
	v_mfma_f32_16x16x32_bf16 v[30:33], v[146:149], v[194:197], v[30:33]
	v_mfma_f32_16x16x32_bf16 v[26:29], v[160:163], v[194:197], v[26:29]
	v_mfma_f32_16x16x32_bf16 v[22:25], v[146:149], v[202:205], v[22:25]
	v_mfma_f32_16x16x32_bf16 v[18:21], v[160:163], v[202:205], v[18:21]
	v_mfma_f32_16x16x32_bf16 v[14:17], v[146:149], v[218:221], v[14:17]
	v_mfma_f32_16x16x32_bf16 v[10:13], v[160:163], v[218:221], v[10:13]
	v_mfma_f32_16x16x32_bf16 v[6:9], v[146:149], v[226:229], v[6:9]
	v_mfma_f32_16x16x32_bf16 v[2:5], v[160:163], v[226:229], v[2:5]
	v_mfma_f32_16x16x32_bf16 v[30:33], v[156:159], v[198:201], v[30:33]
	v_mfma_f32_16x16x32_bf16 v[26:29], v[174:177], v[198:201], v[26:29]
	v_mfma_f32_16x16x32_bf16 v[22:25], v[156:159], v[206:209], v[22:25]
	v_mfma_f32_16x16x32_bf16 v[18:21], v[174:177], v[206:209], v[18:21]
	v_mfma_f32_16x16x32_bf16 v[14:17], v[156:159], v[222:225], v[14:17]
	v_mfma_f32_16x16x32_bf16 v[10:13], v[174:177], v[222:225], v[10:13]
	v_mfma_f32_16x16x32_bf16 v[6:9], v[156:159], v[230:233], v[6:9]
	v_mfma_f32_16x16x32_bf16 v[2:5], v[174:177], v[230:233], v[2:5]
	s_setprio 0
	s_setprio 1
	v_mfma_f32_16x16x32_bf16 v[94:97], v[178:181], v[194:197], v[94:97]
	v_mfma_f32_16x16x32_bf16 v[90:93], v[186:189], v[194:197], v[90:93]
	v_mfma_f32_16x16x32_bf16 v[86:89], v[178:181], v[202:205], v[86:89]
	v_mfma_f32_16x16x32_bf16 v[82:85], v[186:189], v[202:205], v[82:85]
	v_mfma_f32_16x16x32_bf16 v[78:81], v[178:181], v[218:221], v[78:81]
	v_mfma_f32_16x16x32_bf16 v[74:77], v[186:189], v[218:221], v[74:77]
	v_mfma_f32_16x16x32_bf16 v[54:57], v[178:181], v[226:229], v[54:57]
	v_mfma_f32_16x16x32_bf16 v[34:37], v[186:189], v[226:229], v[34:37]
	v_mfma_f32_16x16x32_bf16 v[94:97], v[182:185], v[198:201], v[94:97]
	v_mfma_f32_16x16x32_bf16 v[90:93], v[190:193], v[198:201], v[90:93]
	v_mfma_f32_16x16x32_bf16 v[86:89], v[182:185], v[206:209], v[86:89]
	v_mfma_f32_16x16x32_bf16 v[82:85], v[190:193], v[206:209], v[82:85]
	v_mfma_f32_16x16x32_bf16 v[78:81], v[182:185], v[222:225], v[78:81]
	v_mfma_f32_16x16x32_bf16 v[74:77], v[190:193], v[222:225], v[74:77]
	v_mfma_f32_16x16x32_bf16 v[54:57], v[182:185], v[230:233], v[54:57]
	v_mfma_f32_16x16x32_bf16 v[34:37], v[190:193], v[230:233], v[34:37]
	s_setprio 0
	s_barrier
	s_add_i32 s62, s62, 2
	s_add_u32 s60, s60, 0x100
	s_addc_u32 s61, s61, 0
	s_add_u32 s0, s0, 0x100
	s_addc_u32 s1, s1, 0
	s_cmp_gt_u32 s62, 29
	s_add_u32 s30, s0, 0xfff80080
	s_addc_u32 s31, s1, -1
	s_add_i32 s63, 0, 0x10000
	s_cmp_eq_u32 s62, 28
	s_cselect_b32 s51, s41, s31
	s_cselect_b32 s50, s47, s30
	v_add_u32_e32 v150, s63, v153
	s_cselect_b32 s49, s39, s61
	s_cselect_b32 s48, s55, s60
	s_add_i32 s64, 0, 0x14000
	ds_read_b128 v[146:149], v150
	ds_read_b128 v[156:159], v150 offset:1024
	ds_read_b128 v[160:163], v150 offset:2048
	ds_read_b128 v[174:177], v150 offset:3072
	v_add_u32_e32 v150, s64, v153
	ds_read_b128 v[178:181], v150
	ds_read_b128 v[182:185], v150 offset:1024
	ds_read_b128 v[186:189], v150 offset:2048
	ds_read_b128 v[190:193], v150 offset:3072
	s_add_i32 m0, s9, 0xc000
	ds_read_b128 v[194:197], v155
	ds_read_b128 v[198:201], v155 offset:1024
	ds_read_b128 v[202:205], v155 offset:2048
	ds_read_b128 v[206:209], v155 offset:3072
	ds_read_b128 v[218:221], v155 offset:4096
	ds_read_b128 v[222:225], v155 offset:5120
	ds_read_b128 v[226:229], v155 offset:6144
	ds_read_b128 v[230:233], v155 offset:7168
	global_load_lds_dwordx4 v144, s[0:1]
	s_add_i32 m0, s9, 0xe000
	s_nop 0
	global_load_lds_dwordx4 v142, s[0:1]
	s_waitcnt vmcnt(9)
	s_waitcnt lgkmcnt(0)
	s_barrier
	s_setprio 1
	s_waitcnt lgkmcnt(0)
	v_mfma_f32_16x16x32_bf16 v[70:73], v[146:149], v[194:197], v[70:73]
	v_mfma_f32_16x16x32_bf16 v[66:69], v[160:163], v[194:197], v[66:69]
	s_mov_b64 exec, s[86:87]
	global_store_dwordx4 v168, v[240:243], s[14:15]
	s_mov_b64 exec, -1
	v_mfma_f32_16x16x32_bf16 v[62:65], v[146:149], v[202:205], v[62:65]
	v_mfma_f32_16x16x32_bf16 v[58:61], v[160:163], v[202:205], v[58:61]
	v_mfma_f32_16x16x32_bf16 v[50:53], v[146:149], v[218:221], v[50:53]
	v_mfma_f32_16x16x32_bf16 v[46:49], v[160:163], v[218:221], v[46:49]
	v_mfma_f32_16x16x32_bf16 v[42:45], v[146:149], v[226:229], v[42:45]
	v_mfma_f32_16x16x32_bf16 v[38:41], v[160:163], v[226:229], v[38:41]
	v_mfma_f32_16x16x32_bf16 v[70:73], v[156:159], v[198:201], v[70:73]
	v_mfma_f32_16x16x32_bf16 v[66:69], v[174:177], v[198:201], v[66:69]
	v_mfma_f32_16x16x32_bf16 v[62:65], v[156:159], v[206:209], v[62:65]
	v_mfma_f32_16x16x32_bf16 v[58:61], v[174:177], v[206:209], v[58:61]
	v_mfma_f32_16x16x32_bf16 v[50:53], v[156:159], v[222:225], v[50:53]
	v_mfma_f32_16x16x32_bf16 v[46:49], v[174:177], v[222:225], v[46:49]
	v_mfma_f32_16x16x32_bf16 v[42:45], v[156:159], v[230:233], v[42:45]
	v_mfma_f32_16x16x32_bf16 v[38:41], v[174:177], v[230:233], v[38:41]
	s_setprio 0
	s_setprio 1
	v_mfma_f32_16x16x32_bf16 v[126:129], v[178:181], v[194:197], v[126:129]
	v_mfma_f32_16x16x32_bf16 v[122:125], v[186:189], v[194:197], v[122:125]
	v_mfma_f32_16x16x32_bf16 v[118:121], v[178:181], v[202:205], v[118:121]
	v_mfma_f32_16x16x32_bf16 v[114:117], v[186:189], v[202:205], v[114:117]
	v_mfma_f32_16x16x32_bf16 v[110:113], v[178:181], v[218:221], v[110:113]
	v_mfma_f32_16x16x32_bf16 v[106:109], v[186:189], v[218:221], v[106:109]
	v_mfma_f32_16x16x32_bf16 v[102:105], v[178:181], v[226:229], v[102:105]
	v_mfma_f32_16x16x32_bf16 v[98:101], v[186:189], v[226:229], v[98:101]
	v_mfma_f32_16x16x32_bf16 v[126:129], v[182:185], v[198:201], v[126:129]
	v_mfma_f32_16x16x32_bf16 v[122:125], v[190:193], v[198:201], v[122:125]
	v_mfma_f32_16x16x32_bf16 v[118:121], v[182:185], v[206:209], v[118:121]
	v_mfma_f32_16x16x32_bf16 v[114:117], v[190:193], v[206:209], v[114:117]
	v_mfma_f32_16x16x32_bf16 v[110:113], v[182:185], v[222:225], v[110:113]
	v_mfma_f32_16x16x32_bf16 v[106:109], v[190:193], v[222:225], v[106:109]
	v_mfma_f32_16x16x32_bf16 v[102:105], v[182:185], v[230:233], v[102:105]
	v_mfma_f32_16x16x32_bf16 v[98:101], v[190:193], v[230:233], v[98:101]
	s_setprio 0
	s_barrier
	s_add_i32 s30, s63, s8
	s_mov_b32 m0, s30
	ds_read_b128 v[194:197], v155 offset:16384
	ds_read_b128 v[198:201], v155 offset:17408
	ds_read_b128 v[202:205], v155 offset:18432
	ds_read_b128 v[206:209], v155 offset:19456
	ds_read_b128 v[218:221], v155 offset:20480
	ds_read_b128 v[222:225], v155 offset:21504
	ds_read_b128 v[226:229], v155 offset:22528
	ds_read_b128 v[230:233], v155 offset:23552
	global_load_lds_dwordx4 v134, s[48:49]
	s_add_i32 m0, s30, 0x2000
	s_add_u32 s30, s48, 0x80000
	s_mov_b64 s[82:83], s[48:49]
	s_addc_u32 s31, s49, 0
	s_add_i32 s63, s64, s8
	global_load_lds_dwordx4 v130, s[48:49]
	s_mov_b32 m0, s63
	s_nop 0
	global_load_lds_dwordx4 v134, s[30:31]
	s_add_i32 m0, s63, 0x2000
	s_nop 0
	global_load_lds_dwordx4 v130, s[30:31]
	s_mov_b32 m0, s9
	s_nop 0
	global_load_lds_dwordx4 v136, s[50:51]
	s_mov_b32 m0, s28
	s_nop 0
	global_load_lds_dwordx4 v132, s[50:51]
	s_waitcnt vmcnt(9)
	s_waitcnt lgkmcnt(0)
	s_barrier
	s_setprio 1
	s_waitcnt lgkmcnt(0)
	v_mfma_f32_16x16x32_bf16 v[30:33], v[146:149], v[194:197], v[30:33]
	v_mfma_f32_16x16x32_bf16 v[26:29], v[160:163], v[194:197], v[26:29]
	v_mfma_f32_16x16x32_bf16 v[22:25], v[146:149], v[202:205], v[22:25]
	v_mfma_f32_16x16x32_bf16 v[18:21], v[160:163], v[202:205], v[18:21]
	v_mfma_f32_16x16x32_bf16 v[14:17], v[146:149], v[218:221], v[14:17]
	v_mfma_f32_16x16x32_bf16 v[10:13], v[160:163], v[218:221], v[10:13]
	v_mfma_f32_16x16x32_bf16 v[6:9], v[146:149], v[226:229], v[6:9]
	v_mfma_f32_16x16x32_bf16 v[2:5], v[160:163], v[226:229], v[2:5]
	v_mfma_f32_16x16x32_bf16 v[30:33], v[156:159], v[198:201], v[30:33]
	v_mfma_f32_16x16x32_bf16 v[26:29], v[174:177], v[198:201], v[26:29]
	v_mfma_f32_16x16x32_bf16 v[22:25], v[156:159], v[206:209], v[22:25]
	v_mfma_f32_16x16x32_bf16 v[18:21], v[174:177], v[206:209], v[18:21]
	v_mfma_f32_16x16x32_bf16 v[14:17], v[156:159], v[222:225], v[14:17]
	v_mfma_f32_16x16x32_bf16 v[10:13], v[174:177], v[222:225], v[10:13]
	v_mfma_f32_16x16x32_bf16 v[6:9], v[156:159], v[230:233], v[6:9]
	v_mfma_f32_16x16x32_bf16 v[2:5], v[174:177], v[230:233], v[2:5]
	s_setprio 0
	s_setprio 1
	v_mfma_f32_16x16x32_bf16 v[94:97], v[178:181], v[194:197], v[94:97]
	v_mfma_f32_16x16x32_bf16 v[90:93], v[186:189], v[194:197], v[90:93]
	v_mfma_f32_16x16x32_bf16 v[86:89], v[178:181], v[202:205], v[86:89]
	v_mfma_f32_16x16x32_bf16 v[82:85], v[186:189], v[202:205], v[82:85]
	v_mfma_f32_16x16x32_bf16 v[78:81], v[178:181], v[218:221], v[78:81]
	v_mfma_f32_16x16x32_bf16 v[74:77], v[186:189], v[218:221], v[74:77]
	v_mfma_f32_16x16x32_bf16 v[54:57], v[178:181], v[226:229], v[54:57]
	v_mfma_f32_16x16x32_bf16 v[34:37], v[186:189], v[226:229], v[34:37]
	v_mfma_f32_16x16x32_bf16 v[94:97], v[182:185], v[198:201], v[94:97]
	v_mfma_f32_16x16x32_bf16 v[90:93], v[190:193], v[198:201], v[90:93]
	v_mfma_f32_16x16x32_bf16 v[86:89], v[182:185], v[206:209], v[86:89]
	v_mfma_f32_16x16x32_bf16 v[82:85], v[190:193], v[206:209], v[82:85]
	v_mfma_f32_16x16x32_bf16 v[78:81], v[182:185], v[222:225], v[78:81]
	v_mfma_f32_16x16x32_bf16 v[74:77], v[190:193], v[222:225], v[74:77]
	v_mfma_f32_16x16x32_bf16 v[54:57], v[182:185], v[230:233], v[54:57]
	v_mfma_f32_16x16x32_bf16 v[34:37], v[190:193], v[230:233], v[34:37]
	s_setprio 0
	s_barrier
	s_add_i32 s63, 0, 0x18000
	v_add_u32_e32 v172, s63, v153
	s_add_i32 s64, 0, 0x1c000
	ds_read_b128 v[146:149], v172
	ds_read_b128 v[156:159], v172 offset:1024
	ds_read_b128 v[160:163], v172 offset:2048
	ds_read_b128 v[174:177], v172 offset:3072
	v_add_u32_e32 v172, s64, v153
	ds_read_b128 v[178:181], v172
	ds_read_b128 v[182:185], v172 offset:1024
	ds_read_b128 v[186:189], v172 offset:2048
	ds_read_b128 v[190:193], v172 offset:3072
	s_add_u32 s30, s50, 0x80000
	s_addc_u32 s31, s51, 0
	s_mov_b32 m0, s29
	ds_read_b128 v[194:197], v155 offset:32768
	ds_read_b128 v[198:201], v155 offset:33792
	ds_read_b128 v[202:205], v155 offset:34816
	ds_read_b128 v[206:209], v155 offset:35840
	ds_read_b128 v[218:221], v155 offset:36864
	ds_read_b128 v[222:225], v155 offset:37888
	ds_read_b128 v[226:229], v155 offset:38912
	ds_read_b128 v[230:233], v155 offset:39936
	global_load_lds_dwordx4 v136, s[30:31]
	s_mov_b32 m0, s35
	s_nop 0
	global_load_lds_dwordx4 v132, s[30:31]
	s_waitcnt vmcnt(9)
	s_waitcnt lgkmcnt(0)
	s_barrier
	s_setprio 1
	s_waitcnt lgkmcnt(0)
	v_mfma_f32_16x16x32_bf16 v[70:73], v[146:149], v[194:197], v[70:73]
	v_mfma_f32_16x16x32_bf16 v[66:69], v[160:163], v[194:197], v[66:69]
	s_mov_b64 exec, s[86:87]
	global_store_dwordx4 v168, v[244:247], s[14:15] offset:256
	s_mov_b64 exec, -1
	v_mfma_f32_16x16x32_bf16 v[62:65], v[146:149], v[202:205], v[62:65]
	v_mfma_f32_16x16x32_bf16 v[58:61], v[160:163], v[202:205], v[58:61]
	v_mfma_f32_16x16x32_bf16 v[50:53], v[146:149], v[218:221], v[50:53]
	v_mfma_f32_16x16x32_bf16 v[46:49], v[160:163], v[218:221], v[46:49]
	v_mfma_f32_16x16x32_bf16 v[42:45], v[146:149], v[226:229], v[42:45]
	v_mfma_f32_16x16x32_bf16 v[38:41], v[160:163], v[226:229], v[38:41]
	v_mfma_f32_16x16x32_bf16 v[70:73], v[156:159], v[198:201], v[70:73]
	v_mfma_f32_16x16x32_bf16 v[66:69], v[174:177], v[198:201], v[66:69]
	v_mfma_f32_16x16x32_bf16 v[62:65], v[156:159], v[206:209], v[62:65]
	v_mfma_f32_16x16x32_bf16 v[58:61], v[174:177], v[206:209], v[58:61]
	v_mfma_f32_16x16x32_bf16 v[50:53], v[156:159], v[222:225], v[50:53]
	v_mfma_f32_16x16x32_bf16 v[46:49], v[174:177], v[222:225], v[46:49]
	v_mfma_f32_16x16x32_bf16 v[42:45], v[156:159], v[230:233], v[42:45]
	v_mfma_f32_16x16x32_bf16 v[38:41], v[174:177], v[230:233], v[38:41]
	s_setprio 0
	s_setprio 1
	v_mfma_f32_16x16x32_bf16 v[126:129], v[178:181], v[194:197], v[126:129]
	v_mfma_f32_16x16x32_bf16 v[122:125], v[186:189], v[194:197], v[122:125]
	v_mfma_f32_16x16x32_bf16 v[118:121], v[178:181], v[202:205], v[118:121]
	v_mfma_f32_16x16x32_bf16 v[114:117], v[186:189], v[202:205], v[114:117]
	v_mfma_f32_16x16x32_bf16 v[110:113], v[178:181], v[218:221], v[110:113]
	v_mfma_f32_16x16x32_bf16 v[106:109], v[186:189], v[218:221], v[106:109]
	v_mfma_f32_16x16x32_bf16 v[102:105], v[178:181], v[226:229], v[102:105]
	v_mfma_f32_16x16x32_bf16 v[98:101], v[186:189], v[226:229], v[98:101]
	v_mfma_f32_16x16x32_bf16 v[126:129], v[182:185], v[198:201], v[126:129]
	v_mfma_f32_16x16x32_bf16 v[122:125], v[190:193], v[198:201], v[122:125]
	v_mfma_f32_16x16x32_bf16 v[118:121], v[182:185], v[206:209], v[118:121]
	v_mfma_f32_16x16x32_bf16 v[114:117], v[190:193], v[206:209], v[114:117]
	v_mfma_f32_16x16x32_bf16 v[110:113], v[182:185], v[222:225], v[110:113]
	v_mfma_f32_16x16x32_bf16 v[106:109], v[190:193], v[222:225], v[106:109]
	v_mfma_f32_16x16x32_bf16 v[102:105], v[182:185], v[230:233], v[102:105]
	v_mfma_f32_16x16x32_bf16 v[98:101], v[190:193], v[230:233], v[98:101]
	s_setprio 0
	s_barrier
	s_add_i32 s30, s63, s8
	s_add_i32 m0, s30, 0xffffff80
	ds_read_b128 v[194:197], v155 offset:49152
	ds_read_b128 v[198:201], v155 offset:50176
	ds_read_b128 v[202:205], v155 offset:51200
	ds_read_b128 v[206:209], v155 offset:52224
	ds_read_b128 v[218:221], v155 offset:53248
	ds_read_b128 v[222:225], v155 offset:54272
	ds_read_b128 v[226:229], v155 offset:55296
	ds_read_b128 v[230:233], v155 offset:56320
	global_load_lds_dwordx4 v134, s[48:49] offset:128
	s_add_i32 m0, s30, 0x1f80
	s_add_u32 s30, s48, 0x80080
	s_addc_u32 s31, s49, 0
	s_add_i32 s48, s64, s8
	global_load_lds_dwordx4 v130, s[82:83] offset:128
	s_mov_b32 m0, s48
	s_nop 0
	global_load_lds_dwordx4 v134, s[30:31]
	s_add_i32 m0, s48, 0x2000
	s_nop 0
	global_load_lds_dwordx4 v130, s[30:31]
	s_add_i32 m0, s52, 0xffffff80
	s_nop 0
	global_load_lds_dwordx4 v136, s[50:51] offset:128
	s_add_i32 m0, s53, 0xffffff80
	s_nop 0
	global_load_lds_dwordx4 v132, s[50:51] offset:128
	s_waitcnt vmcnt(9)
	s_waitcnt lgkmcnt(0)
	s_barrier
	s_setprio 1
	s_waitcnt lgkmcnt(0)
	v_mfma_f32_16x16x32_bf16 v[30:33], v[146:149], v[194:197], v[30:33]
	v_mfma_f32_16x16x32_bf16 v[26:29], v[160:163], v[194:197], v[26:29]
	v_mfma_f32_16x16x32_bf16 v[22:25], v[146:149], v[202:205], v[22:25]
	v_mfma_f32_16x16x32_bf16 v[18:21], v[160:163], v[202:205], v[18:21]
	v_mfma_f32_16x16x32_bf16 v[14:17], v[146:149], v[218:221], v[14:17]
	v_mfma_f32_16x16x32_bf16 v[10:13], v[160:163], v[218:221], v[10:13]
	v_mfma_f32_16x16x32_bf16 v[6:9], v[146:149], v[226:229], v[6:9]
	v_mfma_f32_16x16x32_bf16 v[2:5], v[160:163], v[226:229], v[2:5]
	v_mfma_f32_16x16x32_bf16 v[30:33], v[156:159], v[198:201], v[30:33]
	v_mfma_f32_16x16x32_bf16 v[26:29], v[174:177], v[198:201], v[26:29]
	v_mfma_f32_16x16x32_bf16 v[22:25], v[156:159], v[206:209], v[22:25]
	v_mfma_f32_16x16x32_bf16 v[18:21], v[174:177], v[206:209], v[18:21]
	v_mfma_f32_16x16x32_bf16 v[14:17], v[156:159], v[222:225], v[14:17]
	v_mfma_f32_16x16x32_bf16 v[10:13], v[174:177], v[222:225], v[10:13]
	v_mfma_f32_16x16x32_bf16 v[6:9], v[156:159], v[230:233], v[6:9]
	v_mfma_f32_16x16x32_bf16 v[2:5], v[174:177], v[230:233], v[2:5]
	s_setprio 0
	s_setprio 1
	v_mfma_f32_16x16x32_bf16 v[94:97], v[178:181], v[194:197], v[94:97]
	v_mfma_f32_16x16x32_bf16 v[90:93], v[186:189], v[194:197], v[90:93]
	v_mfma_f32_16x16x32_bf16 v[86:89], v[178:181], v[202:205], v[86:89]
	v_mfma_f32_16x16x32_bf16 v[82:85], v[186:189], v[202:205], v[82:85]
	v_mfma_f32_16x16x32_bf16 v[78:81], v[178:181], v[218:221], v[78:81]
	v_mfma_f32_16x16x32_bf16 v[74:77], v[186:189], v[218:221], v[74:77]
	v_mfma_f32_16x16x32_bf16 v[54:57], v[178:181], v[226:229], v[54:57]
	v_mfma_f32_16x16x32_bf16 v[34:37], v[186:189], v[226:229], v[34:37]
	v_mfma_f32_16x16x32_bf16 v[94:97], v[182:185], v[198:201], v[94:97]
	v_mfma_f32_16x16x32_bf16 v[90:93], v[190:193], v[198:201], v[90:93]
	v_mfma_f32_16x16x32_bf16 v[86:89], v[182:185], v[206:209], v[86:89]
	v_mfma_f32_16x16x32_bf16 v[82:85], v[190:193], v[206:209], v[82:85]
	v_mfma_f32_16x16x32_bf16 v[78:81], v[182:185], v[222:225], v[78:81]
	v_mfma_f32_16x16x32_bf16 v[74:77], v[190:193], v[222:225], v[74:77]
	v_mfma_f32_16x16x32_bf16 v[54:57], v[182:185], v[230:233], v[54:57]
	v_mfma_f32_16x16x32_bf16 v[34:37], v[190:193], v[230:233], v[34:37]
	s_setprio 0
	s_barrier
	s_add_i32 s62, s62, 2
	s_add_u32 s60, s60, 0x100
	s_addc_u32 s61, s61, 0
	s_add_u32 s0, s0, 0x100
	s_addc_u32 s1, s1, 0
	s_cmp_gt_u32 s62, 29
	s_add_u32 s30, s0, 0xfff80080
	s_addc_u32 s31, s1, -1
	s_add_i32 s63, 0, 0x10000
	s_cmp_eq_u32 s62, 28
	s_cselect_b32 s51, s41, s31
	s_cselect_b32 s50, s47, s30
	v_add_u32_e32 v150, s63, v153
	s_cselect_b32 s49, s39, s61
	s_cselect_b32 s48, s55, s60
	s_add_i32 s64, 0, 0x14000
	ds_read_b128 v[146:149], v150
	ds_read_b128 v[156:159], v150 offset:1024
	ds_read_b128 v[160:163], v150 offset:2048
	ds_read_b128 v[174:177], v150 offset:3072
	v_add_u32_e32 v150, s64, v153
	ds_read_b128 v[178:181], v150
	ds_read_b128 v[182:185], v150 offset:1024
	ds_read_b128 v[186:189], v150 offset:2048
	ds_read_b128 v[190:193], v150 offset:3072
	s_add_i32 m0, s9, 0xc000
	ds_read_b128 v[194:197], v155
	ds_read_b128 v[198:201], v155 offset:1024
	ds_read_b128 v[202:205], v155 offset:2048
	ds_read_b128 v[206:209], v155 offset:3072
	ds_read_b128 v[218:221], v155 offset:4096
	ds_read_b128 v[222:225], v155 offset:5120
	ds_read_b128 v[226:229], v155 offset:6144
	ds_read_b128 v[230:233], v155 offset:7168
	global_load_lds_dwordx4 v144, s[0:1]
	s_add_i32 m0, s9, 0xe000
	s_nop 0
	global_load_lds_dwordx4 v142, s[0:1]
	s_waitcnt vmcnt(9)
	s_waitcnt lgkmcnt(0)
	s_barrier
	s_setprio 1
	s_waitcnt lgkmcnt(0)
	v_mfma_f32_16x16x32_bf16 v[70:73], v[146:149], v[194:197], v[70:73]
	v_mfma_f32_16x16x32_bf16 v[66:69], v[160:163], v[194:197], v[66:69]
	s_mov_b64 exec, s[86:87]
	global_store_dwordx4 v169, v[236:239], s[14:15]
	s_mov_b64 exec, -1
	v_mfma_f32_16x16x32_bf16 v[62:65], v[146:149], v[202:205], v[62:65]
	v_mfma_f32_16x16x32_bf16 v[58:61], v[160:163], v[202:205], v[58:61]
	v_mfma_f32_16x16x32_bf16 v[50:53], v[146:149], v[218:221], v[50:53]
	v_mfma_f32_16x16x32_bf16 v[46:49], v[160:163], v[218:221], v[46:49]
	v_mfma_f32_16x16x32_bf16 v[42:45], v[146:149], v[226:229], v[42:45]
	v_mfma_f32_16x16x32_bf16 v[38:41], v[160:163], v[226:229], v[38:41]
	v_mfma_f32_16x16x32_bf16 v[70:73], v[156:159], v[198:201], v[70:73]
	v_mfma_f32_16x16x32_bf16 v[66:69], v[174:177], v[198:201], v[66:69]
	v_mfma_f32_16x16x32_bf16 v[62:65], v[156:159], v[206:209], v[62:65]
	v_mfma_f32_16x16x32_bf16 v[58:61], v[174:177], v[206:209], v[58:61]
	v_mfma_f32_16x16x32_bf16 v[50:53], v[156:159], v[222:225], v[50:53]
	v_mfma_f32_16x16x32_bf16 v[46:49], v[174:177], v[222:225], v[46:49]
	v_mfma_f32_16x16x32_bf16 v[42:45], v[156:159], v[230:233], v[42:45]
	v_mfma_f32_16x16x32_bf16 v[38:41], v[174:177], v[230:233], v[38:41]
	s_setprio 0
	s_setprio 1
	v_mfma_f32_16x16x32_bf16 v[126:129], v[178:181], v[194:197], v[126:129]
	v_mfma_f32_16x16x32_bf16 v[122:125], v[186:189], v[194:197], v[122:125]
	v_mfma_f32_16x16x32_bf16 v[118:121], v[178:181], v[202:205], v[118:121]
	v_mfma_f32_16x16x32_bf16 v[114:117], v[186:189], v[202:205], v[114:117]
	v_mfma_f32_16x16x32_bf16 v[110:113], v[178:181], v[218:221], v[110:113]
	v_mfma_f32_16x16x32_bf16 v[106:109], v[186:189], v[218:221], v[106:109]
	v_mfma_f32_16x16x32_bf16 v[102:105], v[178:181], v[226:229], v[102:105]
	v_mfma_f32_16x16x32_bf16 v[98:101], v[186:189], v[226:229], v[98:101]
	v_mfma_f32_16x16x32_bf16 v[126:129], v[182:185], v[198:201], v[126:129]
	v_mfma_f32_16x16x32_bf16 v[122:125], v[190:193], v[198:201], v[122:125]
	v_mfma_f32_16x16x32_bf16 v[118:121], v[182:185], v[206:209], v[118:121]
	v_mfma_f32_16x16x32_bf16 v[114:117], v[190:193], v[206:209], v[114:117]
	v_mfma_f32_16x16x32_bf16 v[110:113], v[182:185], v[222:225], v[110:113]
	v_mfma_f32_16x16x32_bf16 v[106:109], v[190:193], v[222:225], v[106:109]
	v_mfma_f32_16x16x32_bf16 v[102:105], v[182:185], v[230:233], v[102:105]
	v_mfma_f32_16x16x32_bf16 v[98:101], v[190:193], v[230:233], v[98:101]
	s_setprio 0
	s_barrier
	s_add_i32 s30, s63, s8
	s_mov_b32 m0, s30
	ds_read_b128 v[194:197], v155 offset:16384
	ds_read_b128 v[198:201], v155 offset:17408
	ds_read_b128 v[202:205], v155 offset:18432
	ds_read_b128 v[206:209], v155 offset:19456
	ds_read_b128 v[218:221], v155 offset:20480
	ds_read_b128 v[222:225], v155 offset:21504
	ds_read_b128 v[226:229], v155 offset:22528
	ds_read_b128 v[230:233], v155 offset:23552
	global_load_lds_dwordx4 v134, s[48:49]
	s_add_i32 m0, s30, 0x2000
	s_add_u32 s30, s48, 0x80000
	s_mov_b64 s[82:83], s[48:49]
	s_addc_u32 s31, s49, 0
	s_add_i32 s63, s64, s8
	global_load_lds_dwordx4 v130, s[48:49]
	s_mov_b32 m0, s63
	s_nop 0
	global_load_lds_dwordx4 v134, s[30:31]
	s_add_i32 m0, s63, 0x2000
	s_nop 0
	global_load_lds_dwordx4 v130, s[30:31]
	s_mov_b32 m0, s9
	s_nop 0
	global_load_lds_dwordx4 v136, s[50:51]
	s_mov_b32 m0, s28
	s_nop 0
	global_load_lds_dwordx4 v132, s[50:51]
	s_waitcnt vmcnt(9)
	s_waitcnt lgkmcnt(0)
	s_barrier
	s_setprio 1
	s_waitcnt lgkmcnt(0)
	v_mfma_f32_16x16x32_bf16 v[30:33], v[146:149], v[194:197], v[30:33]
	v_mfma_f32_16x16x32_bf16 v[26:29], v[160:163], v[194:197], v[26:29]
	v_mfma_f32_16x16x32_bf16 v[22:25], v[146:149], v[202:205], v[22:25]
	v_mfma_f32_16x16x32_bf16 v[18:21], v[160:163], v[202:205], v[18:21]
	v_mfma_f32_16x16x32_bf16 v[14:17], v[146:149], v[218:221], v[14:17]
	v_mfma_f32_16x16x32_bf16 v[10:13], v[160:163], v[218:221], v[10:13]
	v_mfma_f32_16x16x32_bf16 v[6:9], v[146:149], v[226:229], v[6:9]
	v_mfma_f32_16x16x32_bf16 v[2:5], v[160:163], v[226:229], v[2:5]
	v_mfma_f32_16x16x32_bf16 v[30:33], v[156:159], v[198:201], v[30:33]
	v_mfma_f32_16x16x32_bf16 v[26:29], v[174:177], v[198:201], v[26:29]
	v_mfma_f32_16x16x32_bf16 v[22:25], v[156:159], v[206:209], v[22:25]
	v_mfma_f32_16x16x32_bf16 v[18:21], v[174:177], v[206:209], v[18:21]
	v_mfma_f32_16x16x32_bf16 v[14:17], v[156:159], v[222:225], v[14:17]
	v_mfma_f32_16x16x32_bf16 v[10:13], v[174:177], v[222:225], v[10:13]
	v_mfma_f32_16x16x32_bf16 v[6:9], v[156:159], v[230:233], v[6:9]
	v_mfma_f32_16x16x32_bf16 v[2:5], v[174:177], v[230:233], v[2:5]
	s_setprio 0
	s_setprio 1
	v_mfma_f32_16x16x32_bf16 v[94:97], v[178:181], v[194:197], v[94:97]
	v_mfma_f32_16x16x32_bf16 v[90:93], v[186:189], v[194:197], v[90:93]
	v_mfma_f32_16x16x32_bf16 v[86:89], v[178:181], v[202:205], v[86:89]
	v_mfma_f32_16x16x32_bf16 v[82:85], v[186:189], v[202:205], v[82:85]
	v_mfma_f32_16x16x32_bf16 v[78:81], v[178:181], v[218:221], v[78:81]
	v_mfma_f32_16x16x32_bf16 v[74:77], v[186:189], v[218:221], v[74:77]
	v_mfma_f32_16x16x32_bf16 v[54:57], v[178:181], v[226:229], v[54:57]
	v_mfma_f32_16x16x32_bf16 v[34:37], v[186:189], v[226:229], v[34:37]
	v_mfma_f32_16x16x32_bf16 v[94:97], v[182:185], v[198:201], v[94:97]
	v_mfma_f32_16x16x32_bf16 v[90:93], v[190:193], v[198:201], v[90:93]
	v_mfma_f32_16x16x32_bf16 v[86:89], v[182:185], v[206:209], v[86:89]
	v_mfma_f32_16x16x32_bf16 v[82:85], v[190:193], v[206:209], v[82:85]
	v_mfma_f32_16x16x32_bf16 v[78:81], v[182:185], v[222:225], v[78:81]
	v_mfma_f32_16x16x32_bf16 v[74:77], v[190:193], v[222:225], v[74:77]
	v_mfma_f32_16x16x32_bf16 v[54:57], v[182:185], v[230:233], v[54:57]
	v_mfma_f32_16x16x32_bf16 v[34:37], v[190:193], v[230:233], v[34:37]
	s_setprio 0
	s_barrier
	s_add_i32 s63, 0, 0x18000
	v_add_u32_e32 v172, s63, v153
	s_add_i32 s64, 0, 0x1c000
	ds_read_b128 v[146:149], v172
	ds_read_b128 v[156:159], v172 offset:1024
	ds_read_b128 v[160:163], v172 offset:2048
	ds_read_b128 v[174:177], v172 offset:3072
	v_add_u32_e32 v172, s64, v153
	ds_read_b128 v[178:181], v172
	ds_read_b128 v[182:185], v172 offset:1024
	ds_read_b128 v[186:189], v172 offset:2048
	ds_read_b128 v[190:193], v172 offset:3072
	s_add_u32 s30, s50, 0x80000
	s_addc_u32 s31, s51, 0
	s_mov_b32 m0, s29
	ds_read_b128 v[194:197], v155 offset:32768
	ds_read_b128 v[198:201], v155 offset:33792
	ds_read_b128 v[202:205], v155 offset:34816
	ds_read_b128 v[206:209], v155 offset:35840
	ds_read_b128 v[218:221], v155 offset:36864
	ds_read_b128 v[222:225], v155 offset:37888
	ds_read_b128 v[226:229], v155 offset:38912
	ds_read_b128 v[230:233], v155 offset:39936
	global_load_lds_dwordx4 v136, s[30:31]
	s_mov_b32 m0, s35
	s_nop 0
	global_load_lds_dwordx4 v132, s[30:31]
	s_waitcnt vmcnt(9)
	s_waitcnt lgkmcnt(0)
	s_barrier
	s_setprio 1
	s_waitcnt lgkmcnt(0)
	v_mfma_f32_16x16x32_bf16 v[70:73], v[146:149], v[194:197], v[70:73]
	v_mfma_f32_16x16x32_bf16 v[66:69], v[160:163], v[194:197], v[66:69]
	s_mov_b64 exec, s[86:87]
	global_store_dwordx4 v169, v[248:251], s[14:15] offset:256
	s_mov_b64 exec, -1
	v_mfma_f32_16x16x32_bf16 v[62:65], v[146:149], v[202:205], v[62:65]
	v_mfma_f32_16x16x32_bf16 v[58:61], v[160:163], v[202:205], v[58:61]
	v_mfma_f32_16x16x32_bf16 v[50:53], v[146:149], v[218:221], v[50:53]
	v_mfma_f32_16x16x32_bf16 v[46:49], v[160:163], v[218:221], v[46:49]
	v_mfma_f32_16x16x32_bf16 v[42:45], v[146:149], v[226:229], v[42:45]
	v_mfma_f32_16x16x32_bf16 v[38:41], v[160:163], v[226:229], v[38:41]
	v_mfma_f32_16x16x32_bf16 v[70:73], v[156:159], v[198:201], v[70:73]
	v_mfma_f32_16x16x32_bf16 v[66:69], v[174:177], v[198:201], v[66:69]
	v_mfma_f32_16x16x32_bf16 v[62:65], v[156:159], v[206:209], v[62:65]
	v_mfma_f32_16x16x32_bf16 v[58:61], v[174:177], v[206:209], v[58:61]
	v_mfma_f32_16x16x32_bf16 v[50:53], v[156:159], v[222:225], v[50:53]
	v_mfma_f32_16x16x32_bf16 v[46:49], v[174:177], v[222:225], v[46:49]
	v_mfma_f32_16x16x32_bf16 v[42:45], v[156:159], v[230:233], v[42:45]
	v_mfma_f32_16x16x32_bf16 v[38:41], v[174:177], v[230:233], v[38:41]
	s_setprio 0
	s_setprio 1
	v_mfma_f32_16x16x32_bf16 v[126:129], v[178:181], v[194:197], v[126:129]
	v_mfma_f32_16x16x32_bf16 v[122:125], v[186:189], v[194:197], v[122:125]
	v_mfma_f32_16x16x32_bf16 v[118:121], v[178:181], v[202:205], v[118:121]
	v_mfma_f32_16x16x32_bf16 v[114:117], v[186:189], v[202:205], v[114:117]
	v_mfma_f32_16x16x32_bf16 v[110:113], v[178:181], v[218:221], v[110:113]
	v_mfma_f32_16x16x32_bf16 v[106:109], v[186:189], v[218:221], v[106:109]
	v_mfma_f32_16x16x32_bf16 v[102:105], v[178:181], v[226:229], v[102:105]
	v_mfma_f32_16x16x32_bf16 v[98:101], v[186:189], v[226:229], v[98:101]
	v_mfma_f32_16x16x32_bf16 v[126:129], v[182:185], v[198:201], v[126:129]
	v_mfma_f32_16x16x32_bf16 v[122:125], v[190:193], v[198:201], v[122:125]
	v_mfma_f32_16x16x32_bf16 v[118:121], v[182:185], v[206:209], v[118:121]
	v_mfma_f32_16x16x32_bf16 v[114:117], v[190:193], v[206:209], v[114:117]
	v_mfma_f32_16x16x32_bf16 v[110:113], v[182:185], v[222:225], v[110:113]
	v_mfma_f32_16x16x32_bf16 v[106:109], v[190:193], v[222:225], v[106:109]
	v_mfma_f32_16x16x32_bf16 v[102:105], v[182:185], v[230:233], v[102:105]
	v_mfma_f32_16x16x32_bf16 v[98:101], v[190:193], v[230:233], v[98:101]
	s_setprio 0
	s_barrier
	s_add_i32 s30, s63, s8
	s_add_i32 m0, s30, 0xffffff80
	ds_read_b128 v[194:197], v155 offset:49152
	ds_read_b128 v[198:201], v155 offset:50176
	ds_read_b128 v[202:205], v155 offset:51200
	ds_read_b128 v[206:209], v155 offset:52224
	ds_read_b128 v[218:221], v155 offset:53248
	ds_read_b128 v[222:225], v155 offset:54272
	ds_read_b128 v[226:229], v155 offset:55296
	ds_read_b128 v[230:233], v155 offset:56320
	global_load_lds_dwordx4 v134, s[48:49] offset:128
	s_add_i32 m0, s30, 0x1f80
	s_add_u32 s30, s48, 0x80080
	s_addc_u32 s31, s49, 0
	s_add_i32 s48, s64, s8
	global_load_lds_dwordx4 v130, s[82:83] offset:128
	s_mov_b32 m0, s48
	s_nop 0
	global_load_lds_dwordx4 v134, s[30:31]
	s_add_i32 m0, s48, 0x2000
	s_nop 0
	global_load_lds_dwordx4 v130, s[30:31]
	s_add_i32 m0, s52, 0xffffff80
	s_nop 0
	global_load_lds_dwordx4 v136, s[50:51] offset:128
	s_add_i32 m0, s53, 0xffffff80
	s_nop 0
	global_load_lds_dwordx4 v132, s[50:51] offset:128
	s_waitcnt vmcnt(9)
	s_waitcnt lgkmcnt(0)
	s_barrier
	s_setprio 1
	s_waitcnt lgkmcnt(0)
	v_mfma_f32_16x16x32_bf16 v[30:33], v[146:149], v[194:197], v[30:33]
	v_mfma_f32_16x16x32_bf16 v[26:29], v[160:163], v[194:197], v[26:29]
	v_mfma_f32_16x16x32_bf16 v[22:25], v[146:149], v[202:205], v[22:25]
	v_mfma_f32_16x16x32_bf16 v[18:21], v[160:163], v[202:205], v[18:21]
	v_mfma_f32_16x16x32_bf16 v[14:17], v[146:149], v[218:221], v[14:17]
	v_mfma_f32_16x16x32_bf16 v[10:13], v[160:163], v[218:221], v[10:13]
	v_mfma_f32_16x16x32_bf16 v[6:9], v[146:149], v[226:229], v[6:9]
	v_mfma_f32_16x16x32_bf16 v[2:5], v[160:163], v[226:229], v[2:5]
	v_mfma_f32_16x16x32_bf16 v[30:33], v[156:159], v[198:201], v[30:33]
	v_mfma_f32_16x16x32_bf16 v[26:29], v[174:177], v[198:201], v[26:29]
	v_mfma_f32_16x16x32_bf16 v[22:25], v[156:159], v[206:209], v[22:25]
	v_mfma_f32_16x16x32_bf16 v[18:21], v[174:177], v[206:209], v[18:21]
	v_mfma_f32_16x16x32_bf16 v[14:17], v[156:159], v[222:225], v[14:17]
	v_mfma_f32_16x16x32_bf16 v[10:13], v[174:177], v[222:225], v[10:13]
	v_mfma_f32_16x16x32_bf16 v[6:9], v[156:159], v[230:233], v[6:9]
	v_mfma_f32_16x16x32_bf16 v[2:5], v[174:177], v[230:233], v[2:5]
	s_setprio 0
	s_setprio 1
	v_mfma_f32_16x16x32_bf16 v[94:97], v[178:181], v[194:197], v[94:97]
	v_mfma_f32_16x16x32_bf16 v[90:93], v[186:189], v[194:197], v[90:93]
	v_mfma_f32_16x16x32_bf16 v[86:89], v[178:181], v[202:205], v[86:89]
	v_mfma_f32_16x16x32_bf16 v[82:85], v[186:189], v[202:205], v[82:85]
	v_mfma_f32_16x16x32_bf16 v[78:81], v[178:181], v[218:221], v[78:81]
	v_mfma_f32_16x16x32_bf16 v[74:77], v[186:189], v[218:221], v[74:77]
	v_mfma_f32_16x16x32_bf16 v[54:57], v[178:181], v[226:229], v[54:57]
	v_mfma_f32_16x16x32_bf16 v[34:37], v[186:189], v[226:229], v[34:37]
	v_mfma_f32_16x16x32_bf16 v[94:97], v[182:185], v[198:201], v[94:97]
	v_mfma_f32_16x16x32_bf16 v[90:93], v[190:193], v[198:201], v[90:93]
	v_mfma_f32_16x16x32_bf16 v[86:89], v[182:185], v[206:209], v[86:89]
	v_mfma_f32_16x16x32_bf16 v[82:85], v[190:193], v[206:209], v[82:85]
	v_mfma_f32_16x16x32_bf16 v[78:81], v[182:185], v[222:225], v[78:81]
	v_mfma_f32_16x16x32_bf16 v[74:77], v[190:193], v[222:225], v[74:77]
	v_mfma_f32_16x16x32_bf16 v[54:57], v[182:185], v[230:233], v[54:57]
	v_mfma_f32_16x16x32_bf16 v[34:37], v[190:193], v[230:233], v[34:37]
	s_setprio 0
	s_barrier
	s_add_i32 s62, s62, 2
	s_add_u32 s60, s60, 0x100
	s_addc_u32 s61, s61, 0
	s_add_u32 s0, s0, 0x100
	s_addc_u32 s1, s1, 0
	s_cmp_gt_u32 s62, 29

.LBB0_108:
	s_mov_b32 s98, 0
	s_mov_b64 s[86:87], 0
	v_lshl_add_u32 v146, s46, 8, v152
	s_cmpk_lg_i32 s18, 0x4c
	s_mov_b64 s[0:1], -1
	v_readlane_b32 s61, v254, 34
	s_cbranch_scc0 .LBB0_115
	s_cmp_lt_i32 s18, 60
	s_cbranch_scc0 .LBB0_111
	s_lshl_b32 s78, s18, 22
	v_lshl_add_u32 v174, v146, 9, v0
	v_add_u32_e32 v174, s78, v174
	v_add_u32_e32 v175, 0x2000, v174
	v_add_u32_e32 v176, 0x4000, v174
	v_add_u32_e32 v177, 0x6000, v174
	v_add_u32_e32 v178, 0x10000, v174
	v_add_u32_e32 v179, 0x12000, v174
	v_add_u32_e32 v180, 0x14000, v174
	v_add_u32_e32 v181, 0x16000, v174
	s_mov_b32 s98, 10
	v_mov_b32_e32 v234, v179
	v_mov_b32_e32 v168, v180
	v_mov_b32_e32 v169, v181
	s_and_b32 s0, s18, -4
	s_cmp_eq_u32 s0, 36
	v_pk_mul_f32 v[156:157], v[72:73], s[26:27] op_sel_hi:[1,0]
	v_pk_mul_f32 v[158:159], v[70:71], s[26:27] op_sel_hi:[1,0]
	v_pk_mul_f32 v[160:161], v[68:69], s[26:27] op_sel_hi:[1,0]
	v_pk_mul_f32 v[162:163], v[66:67], s[26:27] op_sel_hi:[1,0]
	s_cselect_b64 vcc, -1, 0
	v_cndmask_b32_e32 v147, v73, v157, vcc
	v_cndmask_b32_e32 v157, v72, v156, vcc
	v_cndmask_b32_e32 v156, v71, v159, vcc
	v_cndmask_b32_e32 v158, v70, v158, vcc
	v_cndmask_b32_e32 v159, v69, v161, vcc
	v_cndmask_b32_e32 v160, v68, v160, vcc
	v_cndmask_b32_e32 v161, v67, v163, vcc
	v_cndmask_b32_e32 v162, v66, v162, vcc
	v_cvt_pk_bf16_f32 v156, v158, v156
	v_cvt_pk_bf16_f32 v157, v157, v147
	v_cvt_pk_bf16_f32 v158, v162, v161
	v_cvt_pk_bf16_f32 v159, v160, v159
	global_store_dwordx4 v174, v[156:159], s[14:15]
	s_nop 1
	v_pk_mul_f32 v[160:161], v[124:125], s[26:27] op_sel_hi:[1,0]
	v_pk_mul_f32 v[162:163], v[122:123], s[26:27] op_sel_hi:[1,0]
	v_pk_mul_f32 v[156:157], v[128:129], s[26:27] op_sel_hi:[1,0]
	v_pk_mul_f32 v[158:159], v[126:127], s[26:27] op_sel_hi:[1,0]
	v_cndmask_b32_e32 v147, v129, v157, vcc
	v_cndmask_b32_e32 v157, v128, v156, vcc
	v_cndmask_b32_e32 v156, v127, v159, vcc
	v_cndmask_b32_e32 v158, v126, v158, vcc
	v_cndmask_b32_e32 v159, v125, v161, vcc
	v_cndmask_b32_e32 v160, v124, v160, vcc
	v_cndmask_b32_e32 v161, v123, v163, vcc
	v_cndmask_b32_e32 v162, v122, v162, vcc
	v_cvt_pk_bf16_f32 v156, v158, v156
	v_cvt_pk_bf16_f32 v157, v157, v147
	v_cvt_pk_bf16_f32 v158, v162, v161
	v_cvt_pk_bf16_f32 v159, v160, v159
	global_store_dwordx4 v174, v[156:159], s[14:15] offset:256
	s_nop 1
	v_pk_mul_f32 v[162:163], v[60:61], s[26:27] op_sel_hi:[1,0]
	v_pk_mul_f32 v[164:165], v[58:59], s[26:27] op_sel_hi:[1,0]
	v_pk_mul_f32 v[156:157], v[64:65], s[26:27] op_sel_hi:[1,0]
	v_pk_mul_f32 v[158:159], v[62:63], s[26:27] op_sel_hi:[1,0]
	v_cndmask_b32_e32 v147, v65, v157, vcc
	v_cndmask_b32_e32 v157, v64, v156, vcc
	v_cndmask_b32_e32 v156, v63, v159, vcc
	v_cndmask_b32_e32 v158, v62, v158, vcc
	v_cndmask_b32_e32 v159, v61, v163, vcc
	v_cndmask_b32_e32 v162, v60, v162, vcc
	v_cndmask_b32_e32 v163, v59, v165, vcc
	v_cndmask_b32_e32 v164, v58, v164, vcc
	v_cvt_pk_bf16_f32 v156, v158, v156
	v_cvt_pk_bf16_f32 v157, v157, v147
	v_cvt_pk_bf16_f32 v158, v164, v163
	v_cvt_pk_bf16_f32 v159, v162, v159
	global_store_dwordx4 v175, v[156:159], s[14:15]
	s_nop 1
	v_pk_mul_f32 v[162:163], v[116:117], s[26:27] op_sel_hi:[1,0]
	v_pk_mul_f32 v[164:165], v[114:115], s[26:27] op_sel_hi:[1,0]
	v_pk_mul_f32 v[156:157], v[120:121], s[26:27] op_sel_hi:[1,0]
	v_pk_mul_f32 v[158:159], v[118:119], s[26:27] op_sel_hi:[1,0]
	v_cndmask_b32_e32 v147, v121, v157, vcc
	v_cndmask_b32_e32 v157, v120, v156, vcc
	v_cndmask_b32_e32 v156, v119, v159, vcc
	v_cndmask_b32_e32 v158, v118, v158, vcc
	v_cndmask_b32_e32 v159, v117, v163, vcc
	v_cndmask_b32_e32 v162, v116, v162, vcc
	v_cndmask_b32_e32 v163, v115, v165, vcc
	v_cndmask_b32_e32 v164, v114, v164, vcc
	v_cvt_pk_bf16_f32 v156, v158, v156
	v_cvt_pk_bf16_f32 v157, v157, v147
	v_cvt_pk_bf16_f32 v158, v164, v163
	v_cvt_pk_bf16_f32 v159, v162, v159
	global_store_dwordx4 v175, v[156:159], s[14:15] offset:256
	s_nop 1
	v_pk_mul_f32 v[162:163], v[48:49], s[26:27] op_sel_hi:[1,0]
	v_pk_mul_f32 v[164:165], v[46:47], s[26:27] op_sel_hi:[1,0]
	v_pk_mul_f32 v[156:157], v[52:53], s[26:27] op_sel_hi:[1,0]
	v_pk_mul_f32 v[158:159], v[50:51], s[26:27] op_sel_hi:[1,0]
	v_cndmask_b32_e32 v147, v53, v157, vcc
	v_cndmask_b32_e32 v157, v52, v156, vcc
	v_cndmask_b32_e32 v156, v51, v159, vcc
	v_cndmask_b32_e32 v158, v50, v158, vcc
	v_cndmask_b32_e32 v159, v49, v163, vcc
	v_cndmask_b32_e32 v162, v48, v162, vcc
	v_cndmask_b32_e32 v163, v47, v165, vcc
	v_cndmask_b32_e32 v164, v46, v164, vcc
	v_cvt_pk_bf16_f32 v156, v158, v156
	v_cvt_pk_bf16_f32 v157, v157, v147
	v_cvt_pk_bf16_f32 v158, v164, v163
	v_cvt_pk_bf16_f32 v159, v162, v159
	global_store_dwordx4 v176, v[156:159], s[14:15]
	s_nop 1
	v_pk_mul_f32 v[162:163], v[108:109], s[26:27] op_sel_hi:[1,0]
	v_pk_mul_f32 v[164:165], v[106:107], s[26:27] op_sel_hi:[1,0]
	v_pk_mul_f32 v[156:157], v[112:113], s[26:27] op_sel_hi:[1,0]
	v_pk_mul_f32 v[158:159], v[110:111], s[26:27] op_sel_hi:[1,0]
	v_cndmask_b32_e32 v147, v113, v157, vcc
	v_cndmask_b32_e32 v157, v112, v156, vcc
	v_cndmask_b32_e32 v156, v111, v159, vcc
	v_cndmask_b32_e32 v158, v110, v158, vcc
	v_cndmask_b32_e32 v159, v109, v163, vcc
	v_cndmask_b32_e32 v162, v108, v162, vcc
	v_cndmask_b32_e32 v163, v107, v165, vcc
	v_cndmask_b32_e32 v164, v106, v164, vcc
	v_cvt_pk_bf16_f32 v156, v158, v156
	v_cvt_pk_bf16_f32 v157, v157, v147
	v_cvt_pk_bf16_f32 v158, v164, v163
	v_cvt_pk_bf16_f32 v159, v162, v159
	global_store_dwordx4 v176, v[156:159], s[14:15] offset:256
	s_nop 1
	v_pk_mul_f32 v[160:161], v[40:41], s[26:27] op_sel_hi:[1,0]
	v_pk_mul_f32 v[162:163], v[38:39], s[26:27] op_sel_hi:[1,0]
	v_pk_mul_f32 v[156:157], v[44:45], s[26:27] op_sel_hi:[1,0]
	v_pk_mul_f32 v[158:159], v[42:43], s[26:27] op_sel_hi:[1,0]
	v_cndmask_b32_e32 v147, v45, v157, vcc
	v_cndmask_b32_e32 v157, v44, v156, vcc
	v_cndmask_b32_e32 v156, v43, v159, vcc
	v_cndmask_b32_e32 v158, v42, v158, vcc
	v_cndmask_b32_e32 v159, v41, v161, vcc
	v_cndmask_b32_e32 v160, v40, v160, vcc
	v_cndmask_b32_e32 v161, v39, v163, vcc
	v_cndmask_b32_e32 v162, v38, v162, vcc
	v_cvt_pk_bf16_f32 v156, v158, v156
	v_cvt_pk_bf16_f32 v157, v157, v147
	v_cvt_pk_bf16_f32 v158, v162, v161
	v_cvt_pk_bf16_f32 v159, v160, v159
	global_store_dwordx4 v177, v[156:159], s[14:15]
	s_nop 1
	v_pk_mul_f32 v[160:161], v[100:101], s[26:27] op_sel_hi:[1,0]
	v_pk_mul_f32 v[162:163], v[98:99], s[26:27] op_sel_hi:[1,0]
	v_pk_mul_f32 v[156:157], v[104:105], s[26:27] op_sel_hi:[1,0]
	v_pk_mul_f32 v[158:159], v[102:103], s[26:27] op_sel_hi:[1,0]
	v_cndmask_b32_e32 v147, v105, v157, vcc
	v_cndmask_b32_e32 v157, v104, v156, vcc
	v_cndmask_b32_e32 v156, v103, v159, vcc
	v_cndmask_b32_e32 v158, v102, v158, vcc
	v_cndmask_b32_e32 v159, v101, v161, vcc
	v_cndmask_b32_e32 v160, v100, v160, vcc
	v_cndmask_b32_e32 v161, v99, v163, vcc
	v_cndmask_b32_e32 v162, v98, v162, vcc
	v_cvt_pk_bf16_f32 v156, v158, v156
	v_cvt_pk_bf16_f32 v157, v157, v147
	v_cvt_pk_bf16_f32 v158, v162, v161
	v_cvt_pk_bf16_f32 v159, v160, v159
	global_store_dwordx4 v177, v[156:159], s[14:15] offset:256
	s_nop 1
	v_pk_mul_f32 v[160:161], v[28:29], s[26:27] op_sel_hi:[1,0]
	v_pk_mul_f32 v[156:157], v[32:33], s[26:27] op_sel_hi:[1,0]
	v_pk_mul_f32 v[158:159], v[30:31], s[26:27] op_sel_hi:[1,0]
	v_pk_mul_f32 v[162:163], v[26:27], s[26:27] op_sel_hi:[1,0]
	v_cndmask_b32_e32 v147, v33, v157, vcc
	v_cndmask_b32_e32 v157, v32, v156, vcc
	v_cndmask_b32_e32 v156, v31, v159, vcc
	v_cndmask_b32_e32 v159, v29, v161, vcc
	v_cndmask_b32_e32 v160, v28, v160, vcc
	v_cndmask_b32_e32 v158, v30, v158, vcc
	v_cndmask_b32_e32 v161, v27, v163, vcc
	v_cndmask_b32_e32 v162, v26, v162, vcc
	v_cvt_pk_bf16_f32 v159, v160, v159
	v_cvt_pk_bf16_f32 v156, v158, v156
	v_cvt_pk_bf16_f32 v157, v157, v147
	v_cvt_pk_bf16_f32 v158, v162, v161
	global_store_dwordx4 v178, v[156:159], s[14:15]
	s_nop 1
	v_pk_mul_f32 v[160:161], v[92:93], s[26:27] op_sel_hi:[1,0]
	v_pk_mul_f32 v[162:163], v[90:91], s[26:27] op_sel_hi:[1,0]
	v_pk_mul_f32 v[156:157], v[96:97], s[26:27] op_sel_hi:[1,0]
	v_pk_mul_f32 v[158:159], v[94:95], s[26:27] op_sel_hi:[1,0]
	v_cndmask_b32_e32 v147, v97, v157, vcc
	v_cndmask_b32_e32 v157, v96, v156, vcc
	v_cndmask_b32_e32 v156, v95, v159, vcc
	v_cndmask_b32_e32 v158, v94, v158, vcc
	v_cndmask_b32_e32 v159, v93, v161, vcc
	v_cndmask_b32_e32 v160, v92, v160, vcc
	v_cndmask_b32_e32 v161, v91, v163, vcc
	v_cndmask_b32_e32 v162, v90, v162, vcc
	v_cvt_pk_bf16_f32 v156, v158, v156
	v_cvt_pk_bf16_f32 v157, v157, v147
	v_cvt_pk_bf16_f32 v158, v162, v161
	v_cvt_pk_bf16_f32 v159, v160, v159
	global_store_dwordx4 v178, v[156:159], s[14:15] offset:256
	s_nop 1
	v_pk_mul_f32 v[160:161], v[20:21], s[26:27] op_sel_hi:[1,0]
	v_pk_mul_f32 v[156:157], v[24:25], s[26:27] op_sel_hi:[1,0]
	v_pk_mul_f32 v[158:159], v[22:23], s[26:27] op_sel_hi:[1,0]
	v_pk_mul_f32 v[162:163], v[18:19], s[26:27] op_sel_hi:[1,0]
	v_cndmask_b32_e32 v147, v25, v157, vcc
	v_cndmask_b32_e32 v157, v24, v156, vcc
	v_cndmask_b32_e32 v156, v23, v159, vcc
	v_cndmask_b32_e32 v159, v21, v161, vcc
	v_cndmask_b32_e32 v160, v20, v160, vcc
	v_cndmask_b32_e32 v158, v22, v158, vcc
	v_cndmask_b32_e32 v161, v19, v163, vcc
	v_cndmask_b32_e32 v162, v18, v162, vcc
	v_cvt_pk_bf16_f32 v159, v160, v159
	v_cvt_pk_bf16_f32 v156, v158, v156
	v_cvt_pk_bf16_f32 v157, v157, v147
	v_cvt_pk_bf16_f32 v158, v162, v161
	v_mov_b32_e32 v210, v156
	v_mov_b32_e32 v211, v157
	v_mov_b32_e32 v212, v158
	v_mov_b32_e32 v213, v159
	v_pk_mul_f32 v[160:161], v[84:85], s[26:27] op_sel_hi:[1,0]
	v_pk_mul_f32 v[162:163], v[82:83], s[26:27] op_sel_hi:[1,0]
	v_pk_mul_f32 v[156:157], v[88:89], s[26:27] op_sel_hi:[1,0]
	v_pk_mul_f32 v[158:159], v[86:87], s[26:27] op_sel_hi:[1,0]
	v_cndmask_b32_e32 v147, v89, v157, vcc
	v_cndmask_b32_e32 v157, v88, v156, vcc
	v_cndmask_b32_e32 v156, v87, v159, vcc
	v_cndmask_b32_e32 v158, v86, v158, vcc
	v_cndmask_b32_e32 v159, v85, v161, vcc
	v_cndmask_b32_e32 v160, v84, v160, vcc
	v_cndmask_b32_e32 v161, v83, v163, vcc
	v_cndmask_b32_e32 v162, v82, v162, vcc
	v_cvt_pk_bf16_f32 v156, v158, v156
	v_cvt_pk_bf16_f32 v157, v157, v147
	v_cvt_pk_bf16_f32 v158, v162, v161
	v_cvt_pk_bf16_f32 v159, v160, v159
	v_mov_b32_e32 v214, v156
	v_mov_b32_e32 v215, v157
	v_mov_b32_e32 v216, v158
	v_mov_b32_e32 v217, v159
	v_pk_mul_f32 v[160:161], v[12:13], s[26:27] op_sel_hi:[1,0]
	v_pk_mul_f32 v[156:157], v[16:17], s[26:27] op_sel_hi:[1,0]
	v_pk_mul_f32 v[158:159], v[14:15], s[26:27] op_sel_hi:[1,0]
	v_pk_mul_f32 v[162:163], v[10:11], s[26:27] op_sel_hi:[1,0]
	v_cndmask_b32_e32 v147, v17, v157, vcc
	v_cndmask_b32_e32 v157, v16, v156, vcc
	v_cndmask_b32_e32 v156, v15, v159, vcc
	v_cndmask_b32_e32 v159, v13, v161, vcc
	v_cndmask_b32_e32 v160, v12, v160, vcc
	v_cndmask_b32_e32 v158, v14, v158, vcc
	v_cndmask_b32_e32 v161, v11, v163, vcc
	v_cndmask_b32_e32 v162, v10, v162, vcc
	v_cvt_pk_bf16_f32 v159, v160, v159
	v_cvt_pk_bf16_f32 v156, v158, v156
	v_cvt_pk_bf16_f32 v157, v157, v147
	v_cvt_pk_bf16_f32 v158, v162, v161
	v_mov_b32_e32 v240, v156
	v_mov_b32_e32 v241, v157
	v_mov_b32_e32 v242, v158
	v_mov_b32_e32 v243, v159
	v_pk_mul_f32 v[160:161], v[76:77], s[26:27] op_sel_hi:[1,0]
	v_pk_mul_f32 v[162:163], v[74:75], s[26:27] op_sel_hi:[1,0]
	v_pk_mul_f32 v[156:157], v[80:81], s[26:27] op_sel_hi:[1,0]
	v_pk_mul_f32 v[158:159], v[78:79], s[26:27] op_sel_hi:[1,0]
	v_cndmask_b32_e32 v147, v81, v157, vcc
	v_cndmask_b32_e32 v157, v80, v156, vcc
	v_cndmask_b32_e32 v156, v79, v159, vcc
	v_cndmask_b32_e32 v158, v78, v158, vcc
	v_cndmask_b32_e32 v159, v77, v161, vcc
	v_cndmask_b32_e32 v160, v76, v160, vcc
	v_cndmask_b32_e32 v161, v75, v163, vcc
	v_cndmask_b32_e32 v162, v74, v162, vcc
	v_cvt_pk_bf16_f32 v156, v158, v156
	v_cvt_pk_bf16_f32 v157, v157, v147
	v_cvt_pk_bf16_f32 v158, v162, v161
	v_cvt_pk_bf16_f32 v159, v160, v159
	v_mov_b32_e32 v244, v156
	v_mov_b32_e32 v245, v157
	v_mov_b32_e32 v246, v158
	v_mov_b32_e32 v247, v159
	v_pk_mul_f32 v[150:151], v[8:9], s[26:27] op_sel_hi:[1,0]
	v_pk_mul_f32 v[156:157], v[6:7], s[26:27] op_sel_hi:[1,0]
	v_pk_mul_f32 v[158:159], v[4:5], s[26:27] op_sel_hi:[1,0]
	v_pk_mul_f32 v[162:163], v[2:3], s[26:27] op_sel_hi:[1,0]
	v_cndmask_b32_e32 v147, v9, v151, vcc
	v_cndmask_b32_e32 v150, v8, v150, vcc
	v_cndmask_b32_e32 v151, v7, v157, vcc
	v_cndmask_b32_e32 v156, v6, v156, vcc
	v_cndmask_b32_e32 v159, v5, v159, vcc
	v_cndmask_b32_e32 v164, v4, v158, vcc
	v_cndmask_b32_e32 v158, v3, v163, vcc
	v_cndmask_b32_e32 v162, v2, v162, vcc
	v_cvt_pk_bf16_f32 v156, v156, v151
	v_cvt_pk_bf16_f32 v157, v150, v147
	v_cvt_pk_bf16_f32 v158, v162, v158
	v_cvt_pk_bf16_f32 v159, v164, v159
	v_mov_b32_e32 v236, v156
	v_mov_b32_e32 v237, v157
	v_mov_b32_e32 v238, v158
	v_mov_b32_e32 v239, v159
	v_pk_mul_f32 v[148:149], v[56:57], s[26:27] op_sel_hi:[1,0]
	v_pk_mul_f32 v[150:151], v[54:55], s[26:27] op_sel_hi:[1,0]
	v_pk_mul_f32 v[156:157], v[36:37], s[26:27] op_sel_hi:[1,0]
	v_pk_mul_f32 v[158:159], v[34:35], s[26:27] op_sel_hi:[1,0]
	v_cndmask_b32_e32 v147, v57, v149, vcc
	v_cndmask_b32_e32 v149, v56, v148, vcc
	v_cndmask_b32_e32 v148, v55, v151, vcc
	v_cndmask_b32_e32 v150, v54, v150, vcc
	v_cndmask_b32_e32 v151, v37, v157, vcc
	v_cndmask_b32_e32 v156, v36, v156, vcc
	v_cndmask_b32_e32 v157, v35, v159, vcc
	v_cndmask_b32_e32 v158, v34, v158, vcc
	v_cvt_pk_bf16_f32 v148, v150, v148
	v_cvt_pk_bf16_f32 v149, v149, v147
	v_cvt_pk_bf16_f32 v150, v158, v157
	v_cvt_pk_bf16_f32 v151, v156, v151
	v_mov_b32_e32 v248, v148
	v_mov_b32_e32 v249, v149
	v_mov_b32_e32 v250, v150
	v_mov_b32_e32 v251, v151
	s_mov_b64 s[86:87], -1
	s_mov_b64 s[0:1], 0

.LBB0_121:
	s_mov_b64 exec, s[86:87]
	global_store_dwordx4 v234, v[210:213], s[14:15]
	global_store_dwordx4 v234, v[214:217], s[14:15] offset:256
	global_store_dwordx4 v168, v[240:243], s[14:15]
	global_store_dwordx4 v168, v[244:247], s[14:15] offset:256
	global_store_dwordx4 v169, v[236:239], s[14:15]
	global_store_dwordx4 v169, v[248:251], s[14:15] offset:256
	s_mov_b64 exec, -1
	s_nop 7
	v_mov_b32_e32 v168, 0x260
	v_mov_b32_e32 v169, 0x41b17218
	v_mov_b32_e32 v234, 0x3727c5ac
	v_mov_b64_e32 v[236:237], 0x100
	v_mov_b64_e32 v[238:239], 0xff
	v_mov_b32_e32 v250, 0xff800000
	s_waitcnt vmcnt(0)
	s_barrier
